# adds: attention phase runs waves 4-7 at static s_setprio 1
# speedup vs baseline: 1.0077x; 1.0045x over previous
; __global__ void __launch_bounds__(512, 2) fwd_kernel(Params p) {
;     ...
;         volatile int* misc = (volatile int*)(lds + AT_MISC);
;         for (;;) {
;             if (tid == 0) misc[0] = (int)atomicAdd(cnt, 1u);
;             __syncthreads();
;             const int it = misc[0];
;             __syncthreads();
;             if (it >= 1024 || (p.flags & 8)) break;
;             attn_item(p, lds, it);
.LBB0_309:
	v_readfirstlane_b32 s96, v223
	s_cmp_lt_u32 s96, 4
	s_cbranch_scc1 .Lprio_skip_at
	s_setprio 1

; __global__ void __launch_bounds__(512, 2) fwd_kernel(Params p) {
;     ...
;         if (bid >= 32 && !(p.flags >> 8)) {
;             float* scr = (float*)(lds + wave * 8704);
;             constexpr int I_B = 16 * 64, I_O = 32 * 64, I_GU = 32 * 352, I_DN = 88 * 64;
;             for (int itw = (bid - 32) * 8 + wave; itw < 2 * I_B + I_O + I_GU + I_DN; itw += (G - 32) * 8) {
;                 int r = itw;
;                 if (r < I_B) { const int kb = r / 64, nb = r % 64;
;                     transpose_item(p.in[10] + (size_t)(64 * kb) * 2048 + 32 * nb, 2048, (bf16_t*)(ws + WS_WBG) + (size_t)(32 * nb) * 2048 + 64 * kb, 2048, nullptr, scr, lane); continue; } r -= I_B;
.LBB0_545:
	s_or_b64 exec, exec, s[72:73]
	s_setprio 0
	s_cmp_gt_i32 s2, 31
	s_cselect_b64 s[0:1], -1, 0
	s_cmpk_lt_u32 s30, 0x100
	s_cselect_b64 s[4:5], -1, 0
	s_and_b64 s[0:1], s[0:1], s[4:5]
	s_andn2_b64 vcc, exec, s[0:1]
	s_cbranch_vccnz .LBB0_568
	s_lshl_b32 s0, s2, 3
	s_addk_i32 s0, 0xff00
	v_add_u32_e32 v3, s0, v223
	s_movk_i32 s0, 0x5200
	v_cmp_gt_i32_e32 vcc, s0, v3
	s_and_saveexec_b64 s[0:1], vcc
	s_cbranch_execz .LBB0_567
	s_add_u32 s4, s34, 0x6800000
	v_readlane_b32 s52, v255, 0
	s_movk_i32 s3, 0x2200
	s_addc_u32 s5, s35, 0
	v_readlane_b32 s56, v255, 4
	v_readlane_b32 s57, v255, 5
	v_mad_u32_u24 v0, v223, s3, 0
	v_and_b32_e32 v1, 31, v220
	s_add_u32 s6, s34, 0x3c00000
	v_readlane_b32 s58, v255, 6
	v_readlane_b32 s59, v255, 7
	v_readlane_b32 s60, v255, 8
	v_readlane_b32 s61, v255, 9
	v_readlane_b32 s62, v255, 10
	v_readlane_b32 s63, v255, 11
	v_readlane_b32 s64, v255, 12
	v_readlane_b32 s65, v255, 13
	v_readlane_b32 s66, v255, 14
	v_readlane_b32 s67, v255, 15
	s_mov_b64 s[8:9], s[56:57]
	s_waitcnt vmcnt(0)
	v_lshl_add_u32 v13, v1, 2, v0
	v_lshlrev_b32_e32 v1, 3, v220
	s_addc_u32 s7, s35, 0
	s_mov_b64 s[14:15], s[62:63]
	v_lshrrev_b32_e32 v2, 3, v222
	v_and_b32_e32 v14, 56, v1
	s_mov_b64 s[10:11], s[58:59]
	s_cmp_lg_u64 s[14:15], 0
	v_lshrrev_b32_e32 v9, 5, v222
	v_mul_u32_u24_e32 v4, 0x84, v14
	v_lshlrev_b32_e32 v6, 2, v2
	s_cselect_b64 s[8:9], -1, 0
	s_add_u32 s10, s34, 0x3400000
	s_movk_i32 s3, 0x84
	v_add3_u32 v7, v0, v4, v6
	s_mov_b64 s[12:13], s[60:61]
	v_or_b32_e32 v0, 2, v9
	s_addc_u32 s11, s35, 0
	v_mad_u32_u24 v5, v9, s3, v13
	v_mov_b32_e32 v1, 0
	v_mul_u32_u24_e32 v12, 0x1600, v2
	s_mov_b64 s[16:17], s[64:65]
	v_lshlrev_b32_e32 v2, 11, v2
	s_add_u32 s12, s34, 0x2c00000
	v_mul_u32_u24_e32 v15, 0x84, v0
	v_lshlrev_b32_e32 v0, 2, v9
	s_movk_i32 s3, 0x4000
	v_or_b32_e32 v4, 0x4000, v2
	s_mov_b32 s42, 0x8000
	v_or_b32_e32 v6, 0x8000, v2
	s_mov_b32 s43, 0xc000
	v_or_b32_e32 v8, 0xc000, v2
	s_addc_u32 s13, s35, 0
	s_lshl_b32 s44, s31, 3
	v_lshl_add_u64 v[10:11], s[14:15], 0, v[0:1]
	v_lshlrev_b32_e32 v9, 5, v3
	s_lshl_b32 s45, s31, 8
	s_mov_b32 s46, 0x10000
	s_mov_b32 s47, 0x14000
	s_mov_b32 s50, 0x18000
	s_mov_b32 s51, 0x1c000
	s_mov_b32 s89, 0x20000
	s_mov_b32 s90, 0x24000
	s_mov_b32 s91, 0x28000
	s_mov_b32 s92, 0x2c000
	s_mov_b32 s93, 0x30000
	s_mov_b32 s94, 0x34000
	s_mov_b32 s68, 0x38000
	s_mov_b32 s69, 0x3c000
	s_mov_b32 s70, 0x40000
	s_mov_b32 s71, 0x44000
	s_mov_b32 s72, 0x48000
	s_mov_b32 s73, 0x4c000
	s_mov_b32 s74, 0x50000
	s_mov_b32 s75, 0x54000
	s_mov_b32 s76, 0x58000
	s_mov_b32 s77, 0x5c000
	s_mov_b32 s78, 0x60000
	s_mov_b32 s79, 0x64000
	s_mov_b32 s80, 0x68000
	s_mov_b32 s81, 0x6c000
	s_mov_b32 s82, 0x70000
	s_mov_b32 s83, 0x74000
	s_mov_b32 s84, 0x78000
	s_mov_b32 s85, 0x7c000
	v_lshlrev_b32_e32 v12, 1, v12
	s_mov_b32 s86, 0x16000
	s_movk_i32 s87, 0x5800
	s_mov_b32 s95, 0x11e000
	s_mov_b32 s96, 0x129000
	s_mov_b32 s97, 0x134000
	v_add_u32_e32 v50, v13, v15
	s_movk_i32 s88, 0x51ff
	v_add_u32_e32 v51, 0x400, v5
	v_add_u32_e32 v52, 0x800, v5
	v_add_u32_e32 v53, 0xc00, v5
	v_add_u32_e32 v54, 0x1000, v5
	v_add_u32_e32 v55, 0x1400, v5
	v_add_u32_e32 v56, 0x1800, v5
	v_add_u32_e32 v57, 0x1c00, v5
	v_lshlrev_b32_e32 v14, 1, v14
	v_mov_b32_e32 v58, 6
	s_mov_b64 s[14:15], 0
	s_mov_b64 s[16:17], 0x2c00800
	v_readlane_b32 s53, v255, 1
	v_readlane_b32 s54, v255, 2
	v_readlane_b32 s55, v255, 3
	s_mov_b64 s[18:19], s[66:67]
	s_branch .LBB0_549
